# spatial-gating unit: the 16 gate-input loads of the matrix part issued together with the LayerNorm row loads (one HBM round trip per unit less)
# speedup vs baseline: 1.0308x; 1.0003x over previous
.LBB0_268:
	v_readlane_b32 s6, v254, 60
	v_mov_b32_e32 v58, v176
	s_and_b32 s1, s18, 0xffffff80
	v_mov_b32_e32 v0, s6
	ds_read2_b64 v[4:7], v0 offset1:1
	v_readfirstlane_b32 s7, v58
	s_ashr_i32 s0, s7, 6
	s_lshl_b64 s[8:9], s[4:5], 2
	v_and_b32_e32 v12, 63, v58
	s_waitcnt lgkmcnt(0)
	v_readfirstlane_b32 s6, v4
	v_readfirstlane_b32 s11, v5
	s_add_u32 s10, s6, s8
	s_addc_u32 s11, s11, s9
	v_readfirstlane_b32 s6, v6
	v_readfirstlane_b32 s12, v7
	s_add_u32 s8, s6, s8
	s_addc_u32 s9, s12, s9
	s_lshl_b32 s6, s0, 4
	v_lshlrev_b32_e32 v0, 4, v12
	v_mov_b32_e32 v1, v2
	s_add_i32 s38, s6, s1
	v_lshl_add_u64 v[4:5], s[10:11], 0, v[0:1]
	v_lshl_add_u64 v[0:1], s[8:9], 0, v[0:1]
	s_mul_i32 s8, s38, 0x2600
	s_mul_hi_i32 s1, s38, 0x2600
	s_add_u32 s8, s80, s8
	s_addc_u32 s9, s81, s1
	v_lshlrev_b32_e32 v12, 3, v12
	s_barrier
	global_load_dwordx2 v[34:35], v12, s[8:9] offset:3072
	s_or_b32 s1, s38, 1
	s_mul_hi_i32 s9, s1, 0x2600
	s_mulk_i32 s1, 0x2600
	s_add_u32 s8, s80, s1
	s_addc_u32 s9, s81, s9
	global_load_dwordx2 v[36:37], v12, s[8:9] offset:3072
	s_or_b32 s1, s38, 2
	s_mul_hi_i32 s9, s1, 0x2600
	s_mulk_i32 s1, 0x2600
	s_add_u32 s8, s80, s1
	s_addc_u32 s9, s81, s9
	s_or_b32 s1, s38, 3
	global_load_dwordx2 v[42:43], v12, s[8:9] offset:3072
	s_mul_hi_i32 s9, s1, 0x2600
	s_mulk_i32 s1, 0x2600
	s_add_u32 s8, s80, s1
	s_addc_u32 s9, s81, s9
	s_or_b32 s1, s38, 4
	global_load_dwordx2 v[44:45], v12, s[8:9] offset:3072
	s_mul_hi_i32 s9, s1, 0x2600
	s_mulk_i32 s1, 0x2600
	s_add_u32 s8, s80, s1
	s_addc_u32 s9, s81, s9
	s_or_b32 s1, s38, 5
	global_load_dwordx2 v[30:31], v12, s[8:9] offset:3072
	s_mul_hi_i32 s9, s1, 0x2600
	s_mulk_i32 s1, 0x2600
	s_add_u32 s8, s80, s1
	s_addc_u32 s9, s81, s9
	s_or_b32 s1, s38, 6
	global_load_dwordx2 v[32:33], v12, s[8:9] offset:3072
	s_mul_hi_i32 s9, s1, 0x2600
	s_mulk_i32 s1, 0x2600
	s_add_u32 s8, s80, s1
	s_addc_u32 s9, s81, s9
	s_or_b32 s1, s38, 7
	global_load_dwordx2 v[26:27], v12, s[8:9] offset:3072
	s_mul_hi_i32 s9, s1, 0x2600
	s_mulk_i32 s1, 0x2600
	s_add_u32 s8, s80, s1
	s_addc_u32 s9, s81, s9
	s_or_b32 s1, s38, 8
	global_load_dwordx2 v[28:29], v12, s[8:9] offset:3072
	s_mul_hi_i32 s9, s1, 0x2600
	s_mulk_i32 s1, 0x2600
	s_add_u32 s8, s80, s1
	s_addc_u32 s9, s81, s9
	s_or_b32 s1, s38, 9
	global_load_dwordx2 v[22:23], v12, s[8:9] offset:3072
	s_mul_hi_i32 s9, s1, 0x2600
	s_mulk_i32 s1, 0x2600
	s_add_u32 s8, s80, s1
	s_addc_u32 s9, s81, s9
	s_or_b32 s1, s38, 10
	global_load_dwordx2 v[24:25], v12, s[8:9] offset:3072
	s_mul_hi_i32 s9, s1, 0x2600
	s_mulk_i32 s1, 0x2600
	s_add_u32 s8, s80, s1
	s_addc_u32 s9, s81, s9
	s_or_b32 s1, s38, 11
	global_load_dwordx2 v[18:19], v12, s[8:9] offset:3072
	s_mul_hi_i32 s9, s1, 0x2600
	s_mulk_i32 s1, 0x2600
	s_add_u32 s8, s80, s1
	s_addc_u32 s9, s81, s9
	s_or_b32 s1, s38, 12
	global_load_dwordx2 v[20:21], v12, s[8:9] offset:3072
	s_mul_hi_i32 s9, s1, 0x2600
	s_mulk_i32 s1, 0x2600
	s_add_u32 s8, s80, s1
	s_addc_u32 s9, s81, s9
	s_or_b32 s1, s38, 13
	global_load_dwordx2 v[14:15], v12, s[8:9] offset:3072
	s_mul_hi_i32 s9, s1, 0x2600
	s_mulk_i32 s1, 0x2600
	s_add_u32 s8, s80, s1
	s_addc_u32 s9, s81, s9
	s_or_b32 s1, s38, 14
	global_load_dwordx2 v[16:17], v12, s[8:9] offset:3072
	s_mul_hi_i32 s9, s1, 0x2600
	s_mulk_i32 s1, 0x2600
	s_add_u32 s8, s80, s1
	s_addc_u32 s9, s81, s9
	s_or_b32 s1, s38, 15
	flat_load_dwordx4 v[8:11], v[0:1]
	v_bfe_u32 v206, v176, 4, 2
	v_lshl_or_b32 v206, v206, 2, s38
	v_mul_u32_u24_e32 v206, 0x2600, v206
	v_and_b32_e32 v207, 15, v176
	v_lshl_add_u32 v206, v207, 1, v206
	s_and_b32 s32, s46, 3
	s_lshl_b32 s32, s32, 7
	v_add_u32_e32 v206, s32, v206
	global_load_ushort v190, v206, s[80:81] offset:2560
	global_load_ushort v191, v206, s[80:81] offset:2592
	global_load_ushort v192, v206, s[80:81] offset:2624
	global_load_ushort v193, v206, s[80:81] offset:2656
	v_add_u32_e32 v206, 0x2600, v206
	global_load_ushort v194, v206, s[80:81] offset:2560
	global_load_ushort v195, v206, s[80:81] offset:2592
	global_load_ushort v196, v206, s[80:81] offset:2624
	global_load_ushort v197, v206, s[80:81] offset:2656
	v_add_u32_e32 v206, 0x2600, v206
	global_load_ushort v198, v206, s[80:81] offset:2560
	global_load_ushort v199, v206, s[80:81] offset:2592
	global_load_ushort v200, v206, s[80:81] offset:2624
	global_load_ushort v201, v206, s[80:81] offset:2656
	v_add_u32_e32 v206, 0x2600, v206
	global_load_ushort v202, v206, s[80:81] offset:2560
	global_load_ushort v203, v206, s[80:81] offset:2592
	global_load_ushort v204, v206, s[80:81] offset:2624
	global_load_ushort v205, v206, s[80:81] offset:2656
	s_waitcnt vmcnt(0)
	v_lshlrev_b32_e32 v39, 16, v34
	global_load_dwordx2 v[0:1], v12, s[8:9] offset:3072
	s_mul_hi_i32 s9, s1, 0x2600
	s_mulk_i32 s1, 0x2600
	s_add_u32 s8, s80, s1
	s_addc_u32 s9, s81, s9
	s_lshl_b32 s0, s0, 5
	s_add_i32 s10, s0, 0
	v_cmp_lt_i32_e64 s[0:1], v182, v181
	v_and_b32_e32 v53, 0xffff0000, v34
	v_lshlrev_b32_e32 v38, 2, v58
	v_cndmask_b32_e64 v34, v179, v182, s[0:1]
	v_cmp_lt_i32_e64 s[0:1], v183, v181
	v_lshlrev_b32_e32 v65, 2, v34
	v_and_b32_e32 v59, 60, v38
	v_cndmask_b32_e64 v34, v179, v183, s[0:1]
	v_cmp_lt_i32_e64 s[0:1], v184, v181
	v_lshlrev_b32_e32 v64, 2, v34
	v_lshlrev_b32_e32 v55, 16, v35
	v_cndmask_b32_e64 v34, v179, v184, s[0:1]
	v_cmp_lt_i32_e64 s[0:1], v185, v181
	v_lshlrev_b32_e32 v63, 2, v34
	v_lshlrev_b32_e32 v38, 16, v36
	v_cndmask_b32_e64 v34, v179, v185, s[0:1]
	v_cmp_lt_i32_e64 s[0:1], v186, v181
	v_lshlrev_b32_e32 v62, 2, v34
	v_and_b32_e32 v52, 0xffff0000, v36
	v_cndmask_b32_e64 v34, v179, v186, s[0:1]
	v_cmp_lt_i32_e64 s[0:1], v187, v181
	v_lshlrev_b32_e32 v61, 2, v34
	v_lshlrev_b32_e32 v54, 16, v37
	v_cndmask_b32_e64 v34, v179, v187, s[0:1]
	v_lshlrev_b32_e32 v60, 2, v34
	v_and_b32_e32 v35, 0xffff0000, v35
	v_and_b32_e32 v34, 0xffff0000, v37
	v_pk_add_f32 v[36:37], v[38:39], v[52:53]
	v_pk_add_f32 v[40:41], v[54:55], v[34:35]
	v_lshlrev_b32_e32 v51, 16, v42
	v_pk_add_f32 v[36:37], v[36:37], v[40:41]
	s_nop 1
	v_mov_b32_dpp v41, v37 quad_perm:[1,0,3,2] row_mask:0xf bank_mask:0xf
	v_mov_b32_dpp v40, v36 quad_perm:[1,0,3,2] row_mask:0xf bank_mask:0xf
	v_and_b32_e32 v49, 0xffff0000, v42
	v_lshlrev_b32_e32 v47, 16, v43
	v_lshlrev_b32_e32 v50, 16, v44
	v_and_b32_e32 v48, 0xffff0000, v44
	s_waitcnt lgkmcnt(0)
	v_pk_add_f32 v[36:37], v[36:37], v[40:41]
	s_nop 1
	v_mov_b32_dpp v41, v37 quad_perm:[2,3,0,1] row_mask:0xf bank_mask:0xf
	v_mov_b32_dpp v40, v36 quad_perm:[2,3,0,1] row_mask:0xf bank_mask:0xf
	v_lshlrev_b32_e32 v46, 16, v45
	s_mov_b32 s12, 0x3b800000
	v_and_b32_e32 v43, 0xffff0000, v43
	v_and_b32_e32 v42, 0xffff0000, v45
	s_waitcnt lgkmcnt(0)
	v_pk_add_f32 v[36:37], v[36:37], v[40:41]
	s_nop 1
	v_mov_b32_dpp v41, v37 row_half_mirror row_mask:0xf bank_mask:0xf
	v_mov_b32_dpp v40, v36 row_half_mirror row_mask:0xf bank_mask:0xf
	v_pk_add_f32 v[44:45], v[50:51], v[48:49]
	flat_load_dwordx4 v[4:7], v[4:5]
	v_bfe_u32 v3, v58, 4, 2
	global_load_dwordx2 v[12:13], v12, s[8:9] offset:3072
	s_waitcnt lgkmcnt(0)
	v_pk_add_f32 v[36:37], v[36:37], v[40:41]
	s_nop 1
	v_mov_b32_dpp v41, v37 row_mirror row_mask:0xf bank_mask:0xf
	v_mov_b32_dpp v40, v36 row_mirror row_mask:0xf bank_mask:0xf
	s_and_b32 s47, s46, 3
	v_cmp_eq_u32_e32 vcc, s47, v3
	s_waitcnt lgkmcnt(0)
	v_pk_add_f32 v[36:37], v[36:37], v[40:41]
	v_mov_b32_e32 v41, v37
	s_nop 1
	v_permlane16_swap_b32_e32 v37, v41
	v_mov_b32_e32 v40, v36
	s_nop 1
	v_permlane16_swap_b32_e32 v36, v40
	s_waitcnt lgkmcnt(0)
	v_pk_add_f32 v[36:37], v[36:37], v[40:41]
	v_mov_b32_e32 v41, v37
	s_nop 1
	v_permlane32_swap_b32_e32 v37, v41
	v_mov_b32_e32 v40, v36
	s_nop 1
	v_permlane32_swap_b32_e32 v36, v40
	s_waitcnt lgkmcnt(0)
	v_pk_add_f32 v[56:57], v[36:37], v[40:41]
	s_nop 0
	v_pk_fma_f32 v[40:41], v[56:57], s[12:13], v[38:39] op_sel_hi:[1,0,1] neg_lo:[1,0,0] neg_hi:[1,0,0]
	v_pk_fma_f32 v[38:39], v[56:57], s[12:13], v[52:53] op_sel_hi:[1,0,1] neg_lo:[1,0,0] neg_hi:[1,0,0]
	v_pk_add_f32 v[52:53], v[46:47], v[42:43]
	v_pk_fma_f32 v[34:35], v[56:57], s[12:13], v[34:35] op_sel_hi:[1,0,1] neg_lo:[1,0,0] neg_hi:[1,0,0]
	v_pk_add_f32 v[44:45], v[44:45], v[52:53]
	s_nop 1
	v_mov_b32_dpp v53, v45 quad_perm:[1,0,3,2] row_mask:0xf bank_mask:0xf
	v_mov_b32_dpp v52, v44 quad_perm:[1,0,3,2] row_mask:0xf bank_mask:0xf
	v_pk_fma_f32 v[36:37], v[56:57], s[12:13], v[54:55] op_sel_hi:[1,0,1] neg_lo:[1,0,0] neg_hi:[1,0,0]
	s_waitcnt lgkmcnt(0)
	v_pk_add_f32 v[44:45], v[44:45], v[52:53]
	s_nop 1
	v_mov_b32_dpp v53, v45 quad_perm:[2,3,0,1] row_mask:0xf bank_mask:0xf
	v_mov_b32_dpp v52, v44 quad_perm:[2,3,0,1] row_mask:0xf bank_mask:0xf
	s_waitcnt lgkmcnt(0)
	v_pk_add_f32 v[44:45], v[44:45], v[52:53]
	s_nop 1
	v_mov_b32_dpp v53, v45 row_half_mirror row_mask:0xf bank_mask:0xf
	v_mov_b32_dpp v52, v44 row_half_mirror row_mask:0xf bank_mask:0xf
	s_waitcnt lgkmcnt(0)
	v_pk_add_f32 v[44:45], v[44:45], v[52:53]
	s_nop 1
	v_mov_b32_dpp v53, v45 row_mirror row_mask:0xf bank_mask:0xf
	v_mov_b32_dpp v52, v44 row_mirror row_mask:0xf bank_mask:0xf
	s_waitcnt lgkmcnt(0)
	v_pk_add_f32 v[44:45], v[44:45], v[52:53]
	v_mov_b32_e32 v53, v45
	s_nop 1
	v_permlane16_swap_b32_e32 v45, v53
	v_mov_b32_e32 v52, v44
	s_nop 1
	v_permlane16_swap_b32_e32 v44, v52
	s_waitcnt lgkmcnt(0)
	v_pk_add_f32 v[44:45], v[44:45], v[52:53]
	v_mov_b32_e32 v53, v45
	s_nop 1
	v_permlane32_swap_b32_e32 v45, v53
	v_mov_b32_e32 v52, v44
	s_nop 1
	v_permlane32_swap_b32_e32 v44, v52
	s_waitcnt lgkmcnt(0)
	v_pk_add_f32 v[52:53], v[44:45], v[52:53]
	s_nop 0
	v_pk_fma_f32 v[50:51], v[52:53], s[12:13], v[50:51] op_sel_hi:[1,0,1] neg_lo:[1,0,0] neg_hi:[1,0,0]
	v_pk_fma_f32 v[48:49], v[52:53], s[12:13], v[48:49] op_sel_hi:[1,0,1] neg_lo:[1,0,0] neg_hi:[1,0,0]
	v_pk_fma_f32 v[44:45], v[52:53], s[12:13], v[46:47] op_sel_hi:[1,0,1] neg_lo:[1,0,0] neg_hi:[1,0,0]
	v_pk_fma_f32 v[42:43], v[52:53], s[12:13], v[42:43] op_sel_hi:[1,0,1] neg_lo:[1,0,0] neg_hi:[1,0,0]
	v_pk_mul_f32 v[46:47], v[38:39], v[38:39]
	v_pk_mul_f32 v[52:53], v[34:35], v[34:35]
	v_pk_fma_f32 v[46:47], v[40:41], v[40:41], v[46:47]
	v_pk_fma_f32 v[52:53], v[36:37], v[36:37], v[52:53]
	v_pk_mul_f32 v[54:55], v[42:43], v[42:43]
	v_pk_add_f32 v[46:47], v[46:47], v[52:53]
	s_nop 1
	v_mov_b32_dpp v53, v47 quad_perm:[1,0,3,2] row_mask:0xf bank_mask:0xf
	v_mov_b32_dpp v52, v46 quad_perm:[1,0,3,2] row_mask:0xf bank_mask:0xf
	v_pk_fma_f32 v[54:55], v[44:45], v[44:45], v[54:55]
	s_waitcnt lgkmcnt(0)
	v_pk_add_f32 v[46:47], v[46:47], v[52:53]
	s_nop 1
	v_mov_b32_dpp v53, v47 quad_perm:[2,3,0,1] row_mask:0xf bank_mask:0xf
	v_mov_b32_dpp v52, v46 quad_perm:[2,3,0,1] row_mask:0xf bank_mask:0xf
	s_waitcnt lgkmcnt(0)
	v_pk_add_f32 v[46:47], v[46:47], v[52:53]
	s_nop 1
	v_mov_b32_dpp v53, v47 row_half_mirror row_mask:0xf bank_mask:0xf
	v_mov_b32_dpp v52, v46 row_half_mirror row_mask:0xf bank_mask:0xf
	s_waitcnt lgkmcnt(0)
	v_pk_add_f32 v[46:47], v[46:47], v[52:53]
	s_nop 1
	v_mov_b32_dpp v53, v47 row_mirror row_mask:0xf bank_mask:0xf
	v_mov_b32_dpp v52, v46 row_mirror row_mask:0xf bank_mask:0xf
	s_waitcnt lgkmcnt(0)
	v_pk_add_f32 v[46:47], v[46:47], v[52:53]
	v_mov_b32_e32 v53, v47
	s_nop 1
	v_permlane16_swap_b32_e32 v47, v53
	v_mov_b32_e32 v52, v46
	s_nop 1
	v_permlane16_swap_b32_e32 v46, v52
	s_waitcnt lgkmcnt(0)
	v_pk_add_f32 v[46:47], v[46:47], v[52:53]
	v_pk_mul_f32 v[52:53], v[48:49], v[48:49]
	v_mov_b32_e32 v57, v47
	s_nop 1
	v_permlane32_swap_b32_e32 v47, v57
	v_pk_fma_f32 v[52:53], v[50:51], v[50:51], v[52:53]
	v_mov_b32_e32 v56, v46
	s_nop 1
	v_permlane32_swap_b32_e32 v46, v56
	v_pk_add_f32 v[52:53], v[52:53], v[54:55]
	s_nop 1
	v_mov_b32_dpp v55, v53 quad_perm:[1,0,3,2] row_mask:0xf bank_mask:0xf
	v_mov_b32_dpp v54, v52 quad_perm:[1,0,3,2] row_mask:0xf bank_mask:0xf
	s_waitcnt lgkmcnt(0)
	v_pk_add_f32 v[52:53], v[52:53], v[54:55]
	s_nop 1
	v_mov_b32_dpp v55, v53 quad_perm:[2,3,0,1] row_mask:0xf bank_mask:0xf
	v_mov_b32_dpp v54, v52 quad_perm:[2,3,0,1] row_mask:0xf bank_mask:0xf
	s_waitcnt lgkmcnt(0)
	v_pk_add_f32 v[52:53], v[52:53], v[54:55]
	s_nop 1
	v_mov_b32_dpp v55, v53 row_half_mirror row_mask:0xf bank_mask:0xf
	v_mov_b32_dpp v54, v52 row_half_mirror row_mask:0xf bank_mask:0xf
	s_waitcnt lgkmcnt(0)
	v_pk_add_f32 v[52:53], v[52:53], v[54:55]
	s_nop 1
	v_mov_b32_dpp v55, v53 row_mirror row_mask:0xf bank_mask:0xf
	v_mov_b32_dpp v54, v52 row_mirror row_mask:0xf bank_mask:0xf
	s_waitcnt lgkmcnt(0)
	v_pk_add_f32 v[52:53], v[52:53], v[54:55]
	v_mov_b32_e32 v55, v53
	s_nop 1
	v_permlane16_swap_b32_e32 v53, v55
	v_mov_b32_e32 v54, v52
	s_nop 1
	v_permlane16_swap_b32_e32 v52, v54
	s_waitcnt lgkmcnt(0)
	v_pk_add_f32 v[52:53], v[52:53], v[54:55]
	v_mov_b32_e32 v55, v53
	s_nop 1
	v_permlane32_swap_b32_e32 v53, v55
	v_mov_b32_e32 v54, v52
	s_nop 1
	v_permlane32_swap_b32_e32 v52, v54
	s_and_saveexec_b64 s[8:9], vcc
	s_cbranch_execz .LBB0_270
	s_mov_b32 s0, 0x358637bd
	v_pk_add_f32 v[46:47], v[46:47], v[56:57]
	v_mov_b64_e32 v[56:57], s[0:1]
	v_pk_fma_f32 v[46:47], v[46:47], s[12:13], v[56:57] op_sel_hi:[1,0,0]
	s_movk_i32 s11, 0x110
	v_mul_f32_e32 v66, 0x4b800000, v47
	v_cmp_gt_f32_e64 s[0:1], s34, v47
	s_nop 1
	v_cndmask_b32_e64 v47, v47, v66, s[0:1]
	v_rsq_f32_e32 v47, v47
	v_mov_b32_e32 v66, s10
	v_mad_u32_u24 v66, v59, s11, v66
	v_mul_f32_e32 v67, 0x45800000, v47
	v_cndmask_b32_e64 v47, v47, v67, s[0:1]
	v_mul_f32_e32 v41, v41, v47
	v_mul_f32_e32 v39, v39, v47
	v_mul_f32_e32 v37, v37, v47
	s_waitcnt vmcnt(0)
	v_fma_f32 v41, v4, v41, v8
	v_fma_f32 v39, v5, v39, v9
	v_fma_f32 v37, v6, v37, v10
	v_cvt_pk_bf16_f32 v41, v41, v2
	ds_write_b16 v66, v41
	v_cvt_pk_bf16_f32 v39, v39, v2
	ds_write_b16 v66, v39 offset:272
	v_cvt_pk_bf16_f32 v37, v37, v2
	ds_write_b16 v66, v37 offset:544
	v_mul_f32_e32 v37, 0x4b800000, v46
	v_cmp_gt_f32_e64 s[0:1], s34, v46
	v_mul_f32_e32 v35, v35, v47
	v_fma_f32 v35, v7, v35, v11
	v_cndmask_b32_e64 v37, v46, v37, s[0:1]
	v_rsq_f32_e32 v37, v37
	v_cvt_pk_bf16_f32 v35, v35, v2
	ds_write_b16 v66, v35 offset:816
	v_mul_f32_e32 v35, 0x45800000, v37
	v_cndmask_b32_e64 v35, v37, v35, s[0:1]
	v_mul_f32_e32 v37, v40, v35
	v_fma_f32 v37, v4, v37, v8
	v_cvt_pk_bf16_f32 v37, v37, v2
	ds_write_b16 v66, v37 offset:2
	v_mul_f32_e32 v37, v38, v35
	v_mul_f32_e32 v36, v36, v35
	v_fma_f32 v37, v5, v37, v9
	v_fma_f32 v36, v6, v36, v10
	v_cvt_pk_bf16_f32 v37, v37, v2
	ds_write_b16 v66, v37 offset:274
	v_cvt_pk_bf16_f32 v36, v36, v2
	ds_write_b16 v66, v36 offset:546
	v_mul_f32_e32 v36, v34, v35
	s_waitcnt lgkmcnt(7)
	v_pk_add_f32 v[34:35], v[52:53], v[54:55]
	v_fma_f32 v36, v7, v36, v11
	v_pk_fma_f32 v[34:35], v[34:35], s[12:13], v[56:57] op_sel_hi:[1,0,0]
	v_cvt_pk_bf16_f32 v36, v36, v2
	ds_write_b16 v66, v36 offset:818
	v_mul_f32_e32 v37, 0x4b800000, v35
	v_cmp_gt_f32_e64 s[0:1], s34, v35
	s_nop 1
	v_cndmask_b32_e64 v35, v35, v37, s[0:1]
	v_rsq_f32_e32 v35, v35
	s_nop 0
	v_mul_f32_e32 v36, 0x45800000, v35
	v_cndmask_b32_e64 v35, v35, v36, s[0:1]
	v_mul_f32_e32 v36, v51, v35
	v_fma_f32 v36, v4, v36, v8
	v_cvt_pk_bf16_f32 v36, v36, v2
	ds_write_b16 v66, v36 offset:4
	v_mul_f32_e32 v36, v49, v35
	v_fma_f32 v36, v5, v36, v9
	v_cvt_pk_bf16_f32 v36, v36, v2
	ds_write_b16 v66, v36 offset:276
	v_mul_f32_e32 v36, v45, v35
	v_fma_f32 v36, v6, v36, v10
	v_cvt_pk_bf16_f32 v36, v36, v2
	ds_write_b16 v66, v36 offset:548
	v_mul_f32_e32 v36, 0x4b800000, v34
	v_cmp_gt_f32_e64 s[0:1], s34, v34
	v_mul_f32_e32 v35, v43, v35
	v_fma_f32 v35, v7, v35, v11
	v_cndmask_b32_e64 v34, v34, v36, s[0:1]
	v_rsq_f32_e32 v34, v34
	v_cvt_pk_bf16_f32 v35, v35, v2
	ds_write_b16 v66, v35 offset:820
	v_mul_f32_e32 v35, 0x45800000, v34
	v_cndmask_b32_e64 v34, v34, v35, s[0:1]
	v_mul_f32_e32 v35, v50, v34
	v_fma_f32 v35, v4, v35, v8
	v_cvt_pk_bf16_f32 v35, v35, v2
	ds_write_b16 v66, v35 offset:6
	v_mul_f32_e32 v35, v48, v34
	v_fma_f32 v35, v5, v35, v9
	v_cvt_pk_bf16_f32 v35, v35, v2
	ds_write_b16 v66, v35 offset:278
	v_mul_f32_e32 v35, v44, v34
	v_mul_f32_e32 v34, v42, v34
	v_fma_f32 v35, v6, v35, v10
	v_fma_f32 v34, v7, v34, v11
	v_cvt_pk_bf16_f32 v35, v35, v2
	ds_write_b16 v66, v35 offset:550
	v_cvt_pk_bf16_f32 v34, v34, v2
	ds_write_b16 v66, v34 offset:822

.LBB0_285:
	v_readlane_b32 s7, v254, 61
	s_lshl_b64 s[14:15], s[14:15], 9
	v_lshl_or_b32 v28, v3, 2, s38
	v_mov_b32_e32 v1, s7
	ds_read_b64 v[20:21], v1
	v_mov_b32_e32 v1, v2
	v_or_b32_e32 v32, 1, v28
	v_lshlrev_b32_e32 v26, 1, v40
	v_mov_b32_e32 v27, v2
	s_waitcnt lgkmcnt(0)
	v_readfirstlane_b32 s7, v20
	v_readfirstlane_b32 s22, v21
	s_add_u32 s14, s7, s14
	s_addc_u32 s15, s22, s15
	s_ashr_i32 s7, s6, 31
	s_lshl_b64 s[6:7], s[6:7], 2
	s_add_u32 s6, s14, s6
	s_addc_u32 s7, s15, s7
	v_lshl_add_u64 v[0:1], s[6:7], 0, v[0:1]
	flat_load_dwordx4 v[20:23], v[0:1]
	v_mov_b64_e32 v[0:1], s[80:81]
	s_lshl_b32 s88, s47, 7
	v_mad_i64_i32 v[30:31], s[6:7], v32, s30, v[0:1]
	v_lshl_add_u64 v[30:31], v[30:31], 0, s[88:89]
	v_or_b32_e32 v34, 2, v28
	v_lshl_add_u64 v[36:37], v[30:31], 0, v[26:27]
	v_mad_i64_i32 v[30:31], s[6:7], v34, s30, v[0:1]
	v_lshl_add_u64 v[30:31], v[30:31], 0, s[88:89]
	v_mad_i64_i32 v[24:25], s[6:7], v28, s30, v[0:1]
	v_lshl_add_u64 v[54:55], v[30:31], 0, v[26:27]
	v_or_b32_e32 v30, 3, v28
	v_lshl_add_u64 v[24:25], v[24:25], 0, s[88:89]
	v_mad_i64_i32 v[0:1], s[6:7], v30, s30, v[0:1]
	v_lshl_add_u64 v[24:25], v[24:25], 0, v[26:27]
	v_lshl_add_u64 v[0:1], v[0:1], 0, s[88:89]
	v_lshl_add_u64 v[0:1], v[0:1], 0, v[26:27]
	v_mov_b32_e32 v53, v190
	v_mov_b32_e32 v50, v194
	v_mov_b32_e32 v48, v191
	v_mov_b32_e32 v46, v195
	v_mov_b32_e32 v44, v192
	v_mov_b32_e32 v42, v196
	s_nop 0
	v_mov_b32_e32 v37, v197
	s_nop 0
	v_mov_b32_e32 v39, v193
	v_mov_b32_e32 v52, v198
	v_mov_b32_e32 v51, v202
	v_mov_b32_e32 v49, v199
	v_mov_b32_e32 v47, v203
	v_mov_b32_e32 v45, v200
	v_mov_b32_e32 v43, v204
	v_mov_b32_e32 v36, v205
	v_mov_b32_e32 v38, v201
	v_lshlrev_b32_e32 v0, 3, v3
	v_lshl_add_u32 v0, v0, 1, 0
	v_mul_u32_u24_e32 v1, 0x110, v40
	v_cndmask_b32_e64 v3, 0, 1, s[0:1]
	v_cmp_ne_u32_e64 s[38:39], 1, v3
	s_andn2_b64 vcc, exec, s[0:1]
	v_add_u32_e32 v41, v0, v1
	s_cbranch_vccnz .LBB0_287
	ds_read_b128 v[24:27], v41
	s_waitcnt vmcnt(0) lgkmcnt(0)
	v_mfma_f32_16x16x32_bf16 v[24:27], v[4:7], v[24:27], 0
	v_cndmask_b32_e64 v0, 0, 1, s[8:9]
	v_cmp_ne_u32_e64 s[40:41], 1, v0
	s_andn2_b64 vcc, exec, s[8:9]
	s_cbranch_vccz .LBB0_288
	s_branch .LBB0_289
